# phase 11a token loop rewritten by hand (one gelu/scale/store per token over all pair groups, SALU token addressing, saddr gathers, deferred W2 store)
# baseline (speedup 1.0000x reference)
; DI void phase11a(const Params& P, char* smem_all) {
;     ...
;           const char* rowp = Uq + (long)el[gi] * 1024 + l16 * 16;
; #pragma unroll
;           for (int c = 0; c < 4; ++c) u[gi][c] = *reinterpret_cast<const uint4*>(rowp + c * 256);
;           su[gi] = Us[el[gi]]; sv[gi] = Vs[el[gi]];
;         }
;       }
;       if (!pf) {
;         pf = true;
;         nE0 = Eidx[(long)tn * 128 + lane]; nE1 = Eidx[(long)tn * 128 + 64 + lane];
;         nG0 = G[(long)tn * 128 + lane]; nG1 = G[(long)tn * 128 + 64 + lane];
; #pragma unroll
;         for (int c = 0; c < 4; ++c) nx[c] = *reinterpret_cast<const uint4*>(xq + (long)tn * 1024 + (c * 16 + l16) * 16);
;         nsx = sxp[tn];
;       }
.Lp11a_issued:
	v_lshrrev_b32_e32 v175, 8, v154
	v_and_b32_e32 v175, 0xfffc, v175
	global_load_dword v156, v175, s[32:33]
	global_load_dword v153, v175, s[28:29]
	s_cmp_lg_u32 s12, 0
	s_cbranch_scc1 .Lp11a_later
	s_lshl_b32 s0, s7, 9
	s_add_u32 s8, s38, s0
	s_addc_u32 s9, s39, 0
	global_load_dword v10, v0, s[8:9]
	global_load_dword v11, v0, s[8:9] offset:256
	s_add_u32 s8, s42, s0
	s_addc_u32 s9, s43, 0
	global_load_dword v12, v0, s[8:9]
	global_load_dword v13, v0, s[8:9] offset:256
	s_lshl_b32 s0, s7, 10
	s_add_u32 s8, s62, s0
	s_addc_u32 s9, s63, 0
	global_load_dwordx4 v[32:35], v1, s[8:9]
	global_load_dwordx4 v[36:39], v1, s[8:9] offset:256
	global_load_dwordx4 v[40:43], v1, s[8:9] offset:512
	global_load_dwordx4 v[44:47], v1, s[8:9] offset:768
	s_lshl_b32 s0, s7, 2
	s_add_u32 s8, s30, s0
	s_addc_u32 s9, s31, 0
	s_load_dword s15, s[8:9], 0x0
	s_waitcnt vmcnt(8)
	s_branch .Lp11a_dots
